# attention main loop Q phase: last QK MFMAs of the S3 block issued ahead of the row-max chains (one s_nop 8 instead of two s_nop 9)
# baseline (speedup 1.0000x reference)
.LBB0_665:
	s_mov_b32 s1, s98
	v_add3_u32 v171, s1, v169, v170
	ds_read_b128 v[32:35], v171
	ds_read_b128 v[174:177], v171 offset:32
	s_waitcnt lgkmcnt(1)
	v_mfma_f32_32x32x16_bf16 v[80:95], v[32:35], v[108:111], v[194:209]
	ds_read_b128 v[32:35], v171 offset:6656
	ds_read_b128 v[178:181], v171 offset:6688
	s_waitcnt lgkmcnt(1)
	v_mfma_f32_32x32x16_bf16 v[64:79], v[32:35], v[108:111], v[194:209]
	ds_read_b128 v[32:35], v171 offset:13312
	ds_read_b128 v[182:185], v171 offset:13344
	s_waitcnt lgkmcnt(1)
	v_mfma_f32_32x32x16_bf16 v[48:63], v[32:35], v[108:111], v[194:209]
	ds_read_b128 v[32:35], v171 offset:19968
	ds_read_b128 v[186:189], v171 offset:20000
	v_mfma_f32_32x32x16_bf16 v[80:95], v[174:177], v[104:107], v[80:95]
	s_waitcnt lgkmcnt(1)
	v_mfma_f32_32x32x16_bf16 v[32:47], v[32:35], v[108:111], v[194:209]
	v_mfma_f32_32x32x16_bf16 v[64:79], v[178:181], v[104:107], v[64:79]
	ds_read_b128 v[174:177], v171 offset:64
	ds_read_b128 v[178:181], v171 offset:96
	v_mfma_f32_32x32x16_bf16 v[48:63], v[182:185], v[104:107], v[48:63]
	s_waitcnt lgkmcnt(1)
	v_mfma_f32_32x32x16_bf16 v[80:95], v[174:177], v[100:103], v[80:95]
	ds_read_b128 v[174:177], v171 offset:6720
	ds_read_b128 v[182:185], v171 offset:6752
	v_mfma_f32_32x32x16_bf16 v[32:47], v[186:189], v[104:107], v[32:47]
	s_waitcnt lgkmcnt(1)
	v_mfma_f32_32x32x16_bf16 v[64:79], v[174:177], v[100:103], v[64:79]
	ds_read_b128 v[174:177], v171 offset:13376
	ds_read_b128 v[186:189], v171 offset:13408
	s_waitcnt lgkmcnt(1)
	v_mfma_f32_32x32x16_bf16 v[48:63], v[174:177], v[100:103], v[48:63]
	ds_read_b128 v[174:177], v171 offset:20032
	ds_read_b128 v[190:193], v171 offset:20064
	v_mfma_f32_32x32x16_bf16 v[80:95], v[178:181], v[96:99], v[80:95]
	s_waitcnt lgkmcnt(1)
	v_mfma_f32_32x32x16_bf16 v[32:47], v[174:177], v[100:103], v[32:47]
	ds_read_b128 v[174:177], v171 offset:128
	ds_read_b128 v[178:181], v171 offset:160
	s_waitcnt lgkmcnt(1)
	v_mfma_f32_32x32x16_bf16 v[80:95], v[174:177], v[112:115], v[80:95]
	v_mfma_f32_32x32x16_bf16 v[64:79], v[182:185], v[96:99], v[64:79]
	ds_read_b128 v[174:177], v171 offset:6784
	ds_read_b128 v[182:185], v171 offset:6816
	v_mfma_f32_32x32x16_bf16 v[48:63], v[186:189], v[96:99], v[48:63]
	s_waitcnt lgkmcnt(2)
	v_mfma_f32_32x32x16_bf16 v[80:95], v[178:181], v[116:119], v[80:95]
	s_waitcnt lgkmcnt(1)
	v_mfma_f32_32x32x16_bf16 v[64:79], v[174:177], v[112:115], v[64:79]
	ds_read_b128 v[174:177], v171 offset:13440
	ds_read_b128 v[186:189], v171 offset:13472
	s_nop 7
	v_max_f32_e32 v173, v80, v80
	s_waitcnt lgkmcnt(1)
	v_mfma_f32_32x32x16_bf16 v[48:63], v[174:177], v[112:115], v[48:63]
	ds_read_b128 v[174:177], v171 offset:20096
	ds_read_b128 v[178:181], v171 offset:20128
	v_max_f32_e32 v171, v81, v81
	v_max_f32_e32 v171, v173, v171
	v_max3_f32 v171, v171, v82, v83
	v_max3_f32 v171, v171, v84, v85
	v_max3_f32 v171, v171, v86, v87
	v_max3_f32 v171, v171, v88, v89
	v_mfma_f32_32x32x16_bf16 v[32:47], v[190:193], v[96:99], v[32:47]
	v_max3_f32 v171, v171, v90, v91
	v_max3_f32 v171, v171, v92, v93
	v_max3_f32 v171, v171, v94, v95
	v_mfma_f32_32x32x16_bf16 v[64:79], v[182:185], v[116:119], v[64:79]
	s_waitcnt lgkmcnt(2)
	v_mfma_f32_32x32x16_bf16 v[48:63], v[186:189], v[116:119], v[48:63]
	s_waitcnt lgkmcnt(1)
	v_mfma_f32_32x32x16_bf16 v[32:47], v[174:177], v[112:115], v[32:47]
	s_waitcnt lgkmcnt(0)
	v_mfma_f32_32x32x16_bf16 v[32:47], v[178:181], v[116:119], v[32:47]
	s_nop 8
	v_max3_f32 v171, v171, v64, v65
	v_max3_f32 v171, v171, v66, v67
	v_max3_f32 v171, v171, v68, v69
	v_max3_f32 v171, v171, v70, v71
	v_max3_f32 v171, v171, v72, v73
	v_max3_f32 v171, v171, v74, v75
	v_max3_f32 v171, v171, v76, v77
	v_max3_f32 v171, v171, v78, v79
	v_max3_f32 v171, v171, v48, v49
	v_max3_f32 v171, v171, v50, v51
	v_max3_f32 v171, v171, v52, v53
	v_max3_f32 v171, v171, v54, v55
	v_max3_f32 v171, v171, v56, v57
	v_max3_f32 v171, v171, v58, v59
	v_max3_f32 v171, v171, v60, v61
	v_max3_f32 v171, v171, v62, v63
	v_max3_f32 v171, v171, v32, v33
	v_max3_f32 v171, v171, v34, v35
	v_max3_f32 v171, v171, v36, v37
	v_max3_f32 v171, v171, v38, v39
	v_max3_f32 v171, v171, v40, v41
	v_max3_f32 v171, v171, v42, v43
	v_max3_f32 v171, v171, v44, v45
	v_max3_f32 v171, v171, v46, v47
	v_mov_b32_e32 v173, v171
	s_nop 1
	v_permlane32_swap_b32_e32 v173, v171
	v_max_f32_e32 v171, v171, v173
	v_cmp_gt_f32_e32 vcc, v171, v210
	s_cbranch_vccz .LBB0_668
	s_nop 1
	v_cndmask_b32_e32 v171, 0, v171, vcc
	v_exp_f32_e64 v172, -v171
	v_sub_f32_e32 v194, v194, v171
	v_sub_f32_e32 v195, v195, v171
	v_sub_f32_e32 v196, v196, v171
	v_sub_f32_e32 v197, v197, v171
	v_sub_f32_e32 v198, v198, v171
	v_sub_f32_e32 v199, v199, v171
	v_sub_f32_e32 v200, v200, v171
	v_sub_f32_e32 v201, v201, v171
	v_sub_f32_e32 v202, v202, v171
	v_sub_f32_e32 v203, v203, v171
	v_sub_f32_e32 v204, v204, v171
	v_sub_f32_e32 v205, v205, v171
	v_sub_f32_e32 v206, v206, v171
	v_sub_f32_e32 v207, v207, v171
	v_sub_f32_e32 v208, v208, v171
	v_sub_f32_e32 v209, v209, v171
	v_pk_mul_f32 v[30:31], v[30:31], v[172:173] op_sel_hi:[1,0]
	v_pk_mul_f32 v[28:29], v[28:29], v[172:173] op_sel_hi:[1,0]
	v_pk_mul_f32 v[26:27], v[26:27], v[172:173] op_sel_hi:[1,0]
	v_pk_mul_f32 v[24:25], v[24:25], v[172:173] op_sel_hi:[1,0]
	v_pk_mul_f32 v[22:23], v[22:23], v[172:173] op_sel_hi:[1,0]
	v_pk_mul_f32 v[20:21], v[20:21], v[172:173] op_sel_hi:[1,0]
	v_pk_mul_f32 v[18:19], v[18:19], v[172:173] op_sel_hi:[1,0]
	v_pk_mul_f32 v[16:17], v[16:17], v[172:173] op_sel_hi:[1,0]
	v_pk_mul_f32 v[14:15], v[14:15], v[172:173] op_sel_hi:[1,0]
	v_pk_mul_f32 v[12:13], v[12:13], v[172:173] op_sel_hi:[1,0]
	v_pk_mul_f32 v[10:11], v[10:11], v[172:173] op_sel_hi:[1,0]
	v_pk_mul_f32 v[8:9], v[8:9], v[172:173] op_sel_hi:[1,0]
	v_pk_mul_f32 v[6:7], v[6:7], v[172:173] op_sel_hi:[1,0]
	v_pk_mul_f32 v[4:5], v[4:5], v[172:173] op_sel_hi:[1,0]
	v_pk_mul_f32 v[2:3], v[2:3], v[172:173] op_sel_hi:[1,0]
	v_pk_mul_f32 v[0:1], v[0:1], v[172:173] op_sel_hi:[1,0]
	v_mul_f32_e32 v149, v149, v172
	v_sub_f32_e32 v80, v80, v171
	v_sub_f32_e32 v81, v81, v171
	v_sub_f32_e32 v82, v82, v171
	v_sub_f32_e32 v83, v83, v171
	v_sub_f32_e32 v84, v84, v171
	v_sub_f32_e32 v85, v85, v171
	v_sub_f32_e32 v86, v86, v171
	v_sub_f32_e32 v87, v87, v171
	v_sub_f32_e32 v88, v88, v171
	v_sub_f32_e32 v89, v89, v171
	v_sub_f32_e32 v90, v90, v171
	v_sub_f32_e32 v91, v91, v171
	v_sub_f32_e32 v92, v92, v171
	v_sub_f32_e32 v93, v93, v171
	v_sub_f32_e32 v94, v94, v171
	v_sub_f32_e32 v95, v95, v171
	v_sub_f32_e32 v64, v64, v171
	v_sub_f32_e32 v65, v65, v171
	v_sub_f32_e32 v66, v66, v171
	v_sub_f32_e32 v67, v67, v171
	v_sub_f32_e32 v68, v68, v171
	v_sub_f32_e32 v69, v69, v171
	v_sub_f32_e32 v70, v70, v171
	v_sub_f32_e32 v71, v71, v171
	v_sub_f32_e32 v72, v72, v171
	v_sub_f32_e32 v73, v73, v171
	v_sub_f32_e32 v74, v74, v171
	v_sub_f32_e32 v75, v75, v171
	v_sub_f32_e32 v76, v76, v171
	v_sub_f32_e32 v77, v77, v171
	v_sub_f32_e32 v78, v78, v171
	v_sub_f32_e32 v79, v79, v171
	v_sub_f32_e32 v48, v48, v171
	v_sub_f32_e32 v49, v49, v171
	v_sub_f32_e32 v50, v50, v171
	v_sub_f32_e32 v51, v51, v171
	v_sub_f32_e32 v52, v52, v171
	v_sub_f32_e32 v53, v53, v171
	v_sub_f32_e32 v54, v54, v171
	v_sub_f32_e32 v55, v55, v171
	v_sub_f32_e32 v56, v56, v171
	v_sub_f32_e32 v57, v57, v171
	v_sub_f32_e32 v58, v58, v171
	v_sub_f32_e32 v59, v59, v171
	v_sub_f32_e32 v60, v60, v171
	v_sub_f32_e32 v61, v61, v171
	v_sub_f32_e32 v62, v62, v171
	v_sub_f32_e32 v63, v63, v171
	v_sub_f32_e32 v32, v32, v171
	v_sub_f32_e32 v33, v33, v171
	v_sub_f32_e32 v34, v34, v171
	v_sub_f32_e32 v35, v35, v171
	v_sub_f32_e32 v36, v36, v171
	v_sub_f32_e32 v37, v37, v171
	v_sub_f32_e32 v38, v38, v171
	v_sub_f32_e32 v39, v39, v171
	v_sub_f32_e32 v40, v40, v171
	v_sub_f32_e32 v41, v41, v171
	v_sub_f32_e32 v42, v42, v171
	v_sub_f32_e32 v43, v43, v171
	v_sub_f32_e32 v44, v44, v171
	v_sub_f32_e32 v45, v45, v171
	v_sub_f32_e32 v46, v46, v171
	v_sub_f32_e32 v47, v47, v171
	v_mov_b32_e32 v210, 0x41000000

.LBB0_2129:
	s_mov_b32 s4, s98
	v_add3_u32 v171, s4, v169, v170
	ds_read_b128 v[32:35], v171
	ds_read_b128 v[174:177], v171 offset:32
	s_waitcnt lgkmcnt(1)
	v_mfma_f32_32x32x16_bf16 v[80:95], v[32:35], v[108:111], v[194:209]
	ds_read_b128 v[32:35], v171 offset:6656
	ds_read_b128 v[178:181], v171 offset:6688
	s_waitcnt lgkmcnt(1)
	v_mfma_f32_32x32x16_bf16 v[64:79], v[32:35], v[108:111], v[194:209]
	ds_read_b128 v[32:35], v171 offset:13312
	ds_read_b128 v[182:185], v171 offset:13344
	s_waitcnt lgkmcnt(1)
	v_mfma_f32_32x32x16_bf16 v[48:63], v[32:35], v[108:111], v[194:209]
	ds_read_b128 v[32:35], v171 offset:19968
	ds_read_b128 v[186:189], v171 offset:20000
	v_mfma_f32_32x32x16_bf16 v[80:95], v[174:177], v[104:107], v[80:95]
	s_waitcnt lgkmcnt(1)
	v_mfma_f32_32x32x16_bf16 v[32:47], v[32:35], v[108:111], v[194:209]
	v_mfma_f32_32x32x16_bf16 v[64:79], v[178:181], v[104:107], v[64:79]
	ds_read_b128 v[174:177], v171 offset:64
	ds_read_b128 v[178:181], v171 offset:96
	v_mfma_f32_32x32x16_bf16 v[48:63], v[182:185], v[104:107], v[48:63]
	s_waitcnt lgkmcnt(1)
	v_mfma_f32_32x32x16_bf16 v[80:95], v[174:177], v[100:103], v[80:95]
	ds_read_b128 v[174:177], v171 offset:6720
	ds_read_b128 v[182:185], v171 offset:6752
	v_mfma_f32_32x32x16_bf16 v[32:47], v[186:189], v[104:107], v[32:47]
	s_waitcnt lgkmcnt(1)
	v_mfma_f32_32x32x16_bf16 v[64:79], v[174:177], v[100:103], v[64:79]
	ds_read_b128 v[174:177], v171 offset:13376
	ds_read_b128 v[186:189], v171 offset:13408
	s_waitcnt lgkmcnt(1)
	v_mfma_f32_32x32x16_bf16 v[48:63], v[174:177], v[100:103], v[48:63]
	ds_read_b128 v[174:177], v171 offset:20032
	ds_read_b128 v[190:193], v171 offset:20064
	v_mfma_f32_32x32x16_bf16 v[80:95], v[178:181], v[96:99], v[80:95]
	s_waitcnt lgkmcnt(1)
	v_mfma_f32_32x32x16_bf16 v[32:47], v[174:177], v[100:103], v[32:47]
	ds_read_b128 v[174:177], v171 offset:128
	ds_read_b128 v[178:181], v171 offset:160
	s_waitcnt lgkmcnt(1)
	v_mfma_f32_32x32x16_bf16 v[80:95], v[174:177], v[112:115], v[80:95]
	v_mfma_f32_32x32x16_bf16 v[64:79], v[182:185], v[96:99], v[64:79]
	ds_read_b128 v[174:177], v171 offset:6784
	ds_read_b128 v[182:185], v171 offset:6816
	v_mfma_f32_32x32x16_bf16 v[48:63], v[186:189], v[96:99], v[48:63]
	s_waitcnt lgkmcnt(2)
	v_mfma_f32_32x32x16_bf16 v[80:95], v[178:181], v[116:119], v[80:95]
	s_waitcnt lgkmcnt(1)
	v_mfma_f32_32x32x16_bf16 v[64:79], v[174:177], v[112:115], v[64:79]
	ds_read_b128 v[174:177], v171 offset:13440
	ds_read_b128 v[186:189], v171 offset:13472
	s_nop 7
	v_max_f32_e32 v173, v80, v80
	s_waitcnt lgkmcnt(1)
	v_mfma_f32_32x32x16_bf16 v[48:63], v[174:177], v[112:115], v[48:63]
	ds_read_b128 v[174:177], v171 offset:20096
	ds_read_b128 v[178:181], v171 offset:20128
	v_max_f32_e32 v171, v81, v81
	v_max_f32_e32 v171, v173, v171
	v_max3_f32 v171, v171, v82, v83
	v_max3_f32 v171, v171, v84, v85
	v_max3_f32 v171, v171, v86, v87
	v_max3_f32 v171, v171, v88, v89
	v_mfma_f32_32x32x16_bf16 v[32:47], v[190:193], v[96:99], v[32:47]
	v_max3_f32 v171, v171, v90, v91
	v_max3_f32 v171, v171, v92, v93
	v_max3_f32 v171, v171, v94, v95
	v_mfma_f32_32x32x16_bf16 v[64:79], v[182:185], v[116:119], v[64:79]
	s_waitcnt lgkmcnt(2)
	v_mfma_f32_32x32x16_bf16 v[48:63], v[186:189], v[116:119], v[48:63]
	s_waitcnt lgkmcnt(1)
	v_mfma_f32_32x32x16_bf16 v[32:47], v[174:177], v[112:115], v[32:47]
	s_waitcnt lgkmcnt(0)
	v_mfma_f32_32x32x16_bf16 v[32:47], v[178:181], v[116:119], v[32:47]
	s_nop 8
	v_max3_f32 v171, v171, v64, v65
	v_max3_f32 v171, v171, v66, v67
	v_max3_f32 v171, v171, v68, v69
	v_max3_f32 v171, v171, v70, v71
	v_max3_f32 v171, v171, v72, v73
	v_max3_f32 v171, v171, v74, v75
	v_max3_f32 v171, v171, v76, v77
	v_max3_f32 v171, v171, v78, v79
	v_max3_f32 v171, v171, v48, v49
	v_max3_f32 v171, v171, v50, v51
	v_max3_f32 v171, v171, v52, v53
	v_max3_f32 v171, v171, v54, v55
	v_max3_f32 v171, v171, v56, v57
	v_max3_f32 v171, v171, v58, v59
	v_max3_f32 v171, v171, v60, v61
	v_max3_f32 v171, v171, v62, v63
	v_max3_f32 v171, v171, v32, v33
	v_max3_f32 v171, v171, v34, v35
	v_max3_f32 v171, v171, v36, v37
	v_max3_f32 v171, v171, v38, v39
	v_max3_f32 v171, v171, v40, v41
	v_max3_f32 v171, v171, v42, v43
	v_max3_f32 v171, v171, v44, v45
	v_max3_f32 v171, v171, v46, v47
	v_mov_b32_e32 v173, v171
	s_nop 1
	v_permlane32_swap_b32_e32 v173, v171
	v_max_f32_e32 v171, v171, v173
	v_cmp_gt_f32_e32 vcc, v171, v210
	s_cbranch_vccz .LBB0_2132
	s_nop 1
	v_cndmask_b32_e32 v171, 0, v171, vcc
	v_exp_f32_e64 v172, -v171
	v_sub_f32_e32 v194, v194, v171
	v_sub_f32_e32 v195, v195, v171
	v_sub_f32_e32 v196, v196, v171
	v_sub_f32_e32 v197, v197, v171
	v_sub_f32_e32 v198, v198, v171
	v_sub_f32_e32 v199, v199, v171
	v_sub_f32_e32 v200, v200, v171
	v_sub_f32_e32 v201, v201, v171
	v_sub_f32_e32 v202, v202, v171
	v_sub_f32_e32 v203, v203, v171
	v_sub_f32_e32 v204, v204, v171
	v_sub_f32_e32 v205, v205, v171
	v_sub_f32_e32 v206, v206, v171
	v_sub_f32_e32 v207, v207, v171
	v_sub_f32_e32 v208, v208, v171
	v_sub_f32_e32 v209, v209, v171
	v_pk_mul_f32 v[30:31], v[30:31], v[172:173] op_sel_hi:[1,0]
	v_pk_mul_f32 v[28:29], v[28:29], v[172:173] op_sel_hi:[1,0]
	v_pk_mul_f32 v[26:27], v[26:27], v[172:173] op_sel_hi:[1,0]
	v_pk_mul_f32 v[24:25], v[24:25], v[172:173] op_sel_hi:[1,0]
	v_pk_mul_f32 v[22:23], v[22:23], v[172:173] op_sel_hi:[1,0]
	v_pk_mul_f32 v[20:21], v[20:21], v[172:173] op_sel_hi:[1,0]
	v_pk_mul_f32 v[18:19], v[18:19], v[172:173] op_sel_hi:[1,0]
	v_pk_mul_f32 v[16:17], v[16:17], v[172:173] op_sel_hi:[1,0]
	v_pk_mul_f32 v[14:15], v[14:15], v[172:173] op_sel_hi:[1,0]
	v_pk_mul_f32 v[12:13], v[12:13], v[172:173] op_sel_hi:[1,0]
	v_pk_mul_f32 v[10:11], v[10:11], v[172:173] op_sel_hi:[1,0]
	v_pk_mul_f32 v[8:9], v[8:9], v[172:173] op_sel_hi:[1,0]
	v_pk_mul_f32 v[6:7], v[6:7], v[172:173] op_sel_hi:[1,0]
	v_pk_mul_f32 v[4:5], v[4:5], v[172:173] op_sel_hi:[1,0]
	v_pk_mul_f32 v[2:3], v[2:3], v[172:173] op_sel_hi:[1,0]
	v_pk_mul_f32 v[0:1], v[0:1], v[172:173] op_sel_hi:[1,0]
	v_mul_f32_e32 v149, v149, v172
	v_sub_f32_e32 v80, v80, v171
	v_sub_f32_e32 v81, v81, v171
	v_sub_f32_e32 v82, v82, v171
	v_sub_f32_e32 v83, v83, v171
	v_sub_f32_e32 v84, v84, v171
	v_sub_f32_e32 v85, v85, v171
	v_sub_f32_e32 v86, v86, v171
	v_sub_f32_e32 v87, v87, v171
	v_sub_f32_e32 v88, v88, v171
	v_sub_f32_e32 v89, v89, v171
	v_sub_f32_e32 v90, v90, v171
	v_sub_f32_e32 v91, v91, v171
	v_sub_f32_e32 v92, v92, v171
	v_sub_f32_e32 v93, v93, v171
	v_sub_f32_e32 v94, v94, v171
	v_sub_f32_e32 v95, v95, v171
	v_sub_f32_e32 v64, v64, v171
	v_sub_f32_e32 v65, v65, v171
	v_sub_f32_e32 v66, v66, v171
	v_sub_f32_e32 v67, v67, v171
	v_sub_f32_e32 v68, v68, v171
	v_sub_f32_e32 v69, v69, v171
	v_sub_f32_e32 v70, v70, v171
	v_sub_f32_e32 v71, v71, v171
	v_sub_f32_e32 v72, v72, v171
	v_sub_f32_e32 v73, v73, v171
	v_sub_f32_e32 v74, v74, v171
	v_sub_f32_e32 v75, v75, v171
	v_sub_f32_e32 v76, v76, v171
	v_sub_f32_e32 v77, v77, v171
	v_sub_f32_e32 v78, v78, v171
	v_sub_f32_e32 v79, v79, v171
	v_sub_f32_e32 v48, v48, v171
	v_sub_f32_e32 v49, v49, v171
	v_sub_f32_e32 v50, v50, v171
	v_sub_f32_e32 v51, v51, v171
	v_sub_f32_e32 v52, v52, v171
	v_sub_f32_e32 v53, v53, v171
	v_sub_f32_e32 v54, v54, v171
	v_sub_f32_e32 v55, v55, v171
	v_sub_f32_e32 v56, v56, v171
	v_sub_f32_e32 v57, v57, v171
	v_sub_f32_e32 v58, v58, v171
	v_sub_f32_e32 v59, v59, v171
	v_sub_f32_e32 v60, v60, v171
	v_sub_f32_e32 v61, v61, v171
	v_sub_f32_e32 v62, v62, v171
	v_sub_f32_e32 v63, v63, v171
	v_sub_f32_e32 v32, v32, v171
	v_sub_f32_e32 v33, v33, v171
	v_sub_f32_e32 v34, v34, v171
	v_sub_f32_e32 v35, v35, v171
	v_sub_f32_e32 v36, v36, v171
	v_sub_f32_e32 v37, v37, v171
	v_sub_f32_e32 v38, v38, v171
	v_sub_f32_e32 v39, v39, v171
	v_sub_f32_e32 v40, v40, v171
	v_sub_f32_e32 v41, v41, v171
	v_sub_f32_e32 v42, v42, v171
	v_sub_f32_e32 v43, v43, v171
	v_sub_f32_e32 v44, v44, v171
	v_sub_f32_e32 v45, v45, v171
	v_sub_f32_e32 v46, v46, v171
	v_sub_f32_e32 v47, v47, v171
	v_mov_b32_e32 v210, 0x41000000
